# overlap across segment boundaries (7.2): phase-13 neighbourhood attention (first unit copy) stages the local V^T image right after the last QK MFMA, under the bias/row-max step, instead of after it
# speedup vs baseline: 1.0008x; 1.0008x over previous
.LBB0_1439:
	v_med3_u32 v80, s4, 4, 28
	v_med3_u32 v8, s18, 8, 40
	v_add_u32_e32 v84, -8, v8
	v_sub_u32_e32 v8, v80, v10
	v_lshlrev_b32_e32 v8, 6, v8
	v_add_u32_e32 v78, v8, v84
	v_lshlrev_b32_e32 v8, 1, v79
	v_and_b32_e32 v72, 3, v85
	v_and_or_b32 v8, v8, 24, v72
	v_add_u32_e32 v82, v8, v78
	v_lshlrev_b32_e32 v8, 1, v82
	v_ashrrev_i32_e32 v81, 4, v85
	v_bfe_u32 v12, v82, 3, 2
	v_and_b32_e32 v83, 4, v8
	v_bitop3_b32 v8, v12, v81, v83 bitop3:0x36
	v_lshlrev_b32_e32 v20, 7, v82
	v_lshl_add_u32 v21, v8, 4, 0
	v_add_u32_e32 v87, v21, v20
	s_waitcnt vmcnt(0) lgkmcnt(0)
	s_waitcnt vmcnt(0) lgkmcnt(0)
	s_barrier
	ds_read_b128 v[8:11], v87
	v_add_u32_e32 v86, 4, v81
	v_bitop3_b32 v12, v12, v86, v83 bitop3:0x36
	v_lshl_add_u32 v28, v12, 4, 0
	v_add_u32_e32 v88, v28, v20
	ds_read_b128 v[12:15], v88
	ds_read_b128 v[16:19], v87 offset:8192
	s_waitcnt lgkmcnt(2)
	v_mfma_f32_16x16x32_bf16 v[8:11], v[8:11], v[4:7], 0
	v_or_b32_e32 v29, 0x200, v20
	v_add_u32_e32 v20, v21, v29
	ds_read_b128 v[20:23], v20
	ds_read_b128 v[24:27], v88 offset:8192
	s_waitcnt lgkmcnt(3)
	v_mfma_f32_16x16x32_bf16 v[68:71], v[12:15], v[0:3], v[8:11]
	s_mul_i32 s0, s19, 0x744
	v_subrev_u32_e32 v80, s4, v80
	s_movk_i32 s1, 0x7c
	v_add_u32_e32 v8, v28, v29
	ds_read_b128 v[8:11], v8
	s_waitcnt lgkmcnt(2)
	v_mfma_f32_16x16x32_bf16 v[12:15], v[20:23], v[4:7], 0
	s_add_i32 s0, s0, 0
	v_mul_lo_u32 v80, v80, s1
	v_add_u32_e32 v80, s0, v80
	s_waitcnt lgkmcnt(0)
	v_mfma_f32_16x16x32_bf16 v[64:67], v[8:11], v[0:3], v[12:15]
	v_mfma_f32_16x16x32_bf16 v[8:11], v[16:19], v[4:7], 0
	v_mfma_f32_16x16x32_bf16 v[60:63], v[24:27], v[0:3], v[8:11]
	s_nop 6
	v_add_u32_e32 v8, 0x44, v82
	v_bfe_u32 v13, v8, 3, 2
	v_lshlrev_b32_e32 v12, 7, v8
	v_bitop3_b32 v8, v13, v81, v83 bitop3:0x36
	v_lshlrev_b32_e32 v8, 4, v8
	v_add3_u32 v8, 0, v8, v12
	ds_read_b128 v[8:11], v8
	v_bitop3_b32 v13, v13, v86, v83 bitop3:0x36
	v_lshlrev_b32_e32 v13, 4, v13
	v_add3_u32 v12, 0, v13, v12
	ds_read_b128 v[12:15], v12
	s_waitcnt lgkmcnt(1)
	v_mfma_f32_16x16x32_bf16 v[8:11], v[8:11], v[4:7], 0
	s_waitcnt lgkmcnt(0)
	v_mfma_f32_16x16x32_bf16 v[56:59], v[12:15], v[0:3], v[8:11]
	s_nop 5
	ds_read_b128 v[8:11], v87 offset:16384
	ds_read_b128 v[12:15], v87 offset:24576
	ds_read_b128 v[16:19], v88 offset:16384
	ds_read_b128 v[20:23], v88 offset:24576
	s_waitcnt lgkmcnt(3)
	v_mfma_f32_16x16x32_bf16 v[8:11], v[8:11], v[4:7], 0
	s_waitcnt lgkmcnt(1)
	v_mfma_f32_16x16x32_bf16 v[52:55], v[16:19], v[0:3], v[8:11]
	s_nop 5
	v_add_u32_e32 v8, 0x84, v82
	v_bfe_u32 v17, v8, 3, 2
	v_lshlrev_b32_e32 v16, 7, v8
	v_bitop3_b32 v8, v17, v81, v83 bitop3:0x36
	v_lshlrev_b32_e32 v8, 4, v8
	v_add3_u32 v8, 0, v8, v16
	ds_read_b128 v[8:11], v8
	v_bitop3_b32 v17, v17, v86, v83 bitop3:0x36
	v_lshlrev_b32_e32 v17, 4, v17
	v_add3_u32 v16, 0, v17, v16
	ds_read_b128 v[16:19], v16
	s_waitcnt lgkmcnt(1)
	v_mfma_f32_16x16x32_bf16 v[8:11], v[8:11], v[4:7], 0
	s_waitcnt lgkmcnt(0)
	v_mfma_f32_16x16x32_bf16 v[48:51], v[16:19], v[0:3], v[8:11]
	v_mfma_f32_16x16x32_bf16 v[8:11], v[12:15], v[4:7], 0
	v_mfma_f32_16x16x32_bf16 v[44:47], v[20:23], v[0:3], v[8:11]
	s_nop 6
	v_add_u32_e32 v8, 0xc4, v82
	v_bfe_u32 v13, v8, 3, 2
	v_lshlrev_b32_e32 v12, 7, v8
	v_bitop3_b32 v8, v13, v81, v83 bitop3:0x36
	v_lshlrev_b32_e32 v8, 4, v8
	v_add3_u32 v8, 0, v8, v12
	ds_read_b128 v[8:11], v8
	v_bitop3_b32 v13, v13, v86, v83 bitop3:0x36
	v_lshlrev_b32_e32 v13, 4, v13
	v_add3_u32 v12, 0, v13, v12
	ds_read_b128 v[12:15], v12
	s_waitcnt lgkmcnt(1)
	v_mfma_f32_16x16x32_bf16 v[8:11], v[8:11], v[4:7], 0
	s_waitcnt lgkmcnt(0)
	v_mfma_f32_16x16x32_bf16 v[40:43], v[12:15], v[0:3], v[8:11]
	s_nop 5
	ds_read_b128 v[8:11], v87 offset:32768
	ds_read_b128 v[12:15], v87 offset:40960
	ds_read_b128 v[16:19], v88 offset:32768
	ds_read_b128 v[20:23], v88 offset:40960
	s_waitcnt lgkmcnt(3)
	v_mfma_f32_16x16x32_bf16 v[8:11], v[8:11], v[4:7], 0
	s_waitcnt lgkmcnt(1)
	v_mfma_f32_16x16x32_bf16 v[36:39], v[16:19], v[0:3], v[8:11]
	s_nop 5
	v_add_u32_e32 v8, 0x104, v82
	v_bfe_u32 v17, v8, 3, 2
	v_lshlrev_b32_e32 v16, 7, v8
	v_bitop3_b32 v8, v17, v81, v83 bitop3:0x36
	v_lshlrev_b32_e32 v8, 4, v8
	v_add3_u32 v8, 0, v8, v16
	ds_read_b128 v[8:11], v8
	v_bitop3_b32 v17, v17, v86, v83 bitop3:0x36
	v_lshlrev_b32_e32 v17, 4, v17
	v_add3_u32 v16, 0, v17, v16
	ds_read_b128 v[16:19], v16
	s_waitcnt lgkmcnt(1)
	v_mfma_f32_16x16x32_bf16 v[8:11], v[8:11], v[4:7], 0
	s_waitcnt lgkmcnt(0)
	v_mfma_f32_16x16x32_bf16 v[32:35], v[16:19], v[0:3], v[8:11]
	v_mfma_f32_16x16x32_bf16 v[8:11], v[12:15], v[4:7], 0
	v_mfma_f32_16x16x32_bf16 v[28:31], v[20:23], v[0:3], v[8:11]
	s_nop 6
	v_add_u32_e32 v8, 0x144, v82
	v_bfe_u32 v13, v8, 3, 2
	v_lshlrev_b32_e32 v12, 7, v8
	v_bitop3_b32 v8, v13, v81, v83 bitop3:0x36
	v_lshlrev_b32_e32 v8, 4, v8
	v_add3_u32 v8, 0, v8, v12
	ds_read_b128 v[8:11], v8
	v_bitop3_b32 v13, v13, v86, v83 bitop3:0x36
	v_lshlrev_b32_e32 v13, 4, v13
	v_add3_u32 v12, 0, v13, v12
	ds_read_b128 v[12:15], v12
	s_waitcnt lgkmcnt(1)
	v_mfma_f32_16x16x32_bf16 v[8:11], v[8:11], v[4:7], 0
	s_waitcnt lgkmcnt(0)
	v_mfma_f32_16x16x32_bf16 v[24:27], v[12:15], v[0:3], v[8:11]
	s_nop 5
	ds_read_b128 v[8:11], v87 offset:49152
	ds_read_b128 v[12:15], v87 offset:57344
	ds_read_b128 v[16:19], v88 offset:49152
	ds_read_b128 v[88:91], v88 offset:57344
	v_mov_b32_e32 v87, 0xf149f2ca
	s_waitcnt lgkmcnt(3)
	v_mfma_f32_16x16x32_bf16 v[8:11], v[8:11], v[4:7], 0
	s_waitcnt lgkmcnt(1)
	v_mfma_f32_16x16x32_bf16 v[20:23], v[16:19], v[0:3], v[8:11]
	s_nop 5
	v_add_u32_e32 v8, 0x184, v82
	v_bfe_u32 v17, v8, 3, 2
	v_lshlrev_b32_e32 v16, 7, v8
	v_bitop3_b32 v8, v17, v81, v83 bitop3:0x36
	v_lshlrev_b32_e32 v8, 4, v8
	v_add3_u32 v8, 0, v8, v16
	ds_read_b128 v[8:11], v8
	v_bitop3_b32 v17, v17, v86, v83 bitop3:0x36
	v_lshlrev_b32_e32 v17, 4, v17
	v_add3_u32 v16, 0, v17, v16
	ds_read_b128 v[16:19], v16
	s_waitcnt lgkmcnt(1)
	v_mfma_f32_16x16x32_bf16 v[8:11], v[8:11], v[4:7], 0
	s_waitcnt lgkmcnt(0)
	v_mfma_f32_16x16x32_bf16 v[16:19], v[16:19], v[0:3], v[8:11]
	v_mfma_f32_16x16x32_bf16 v[8:11], v[12:15], v[4:7], 0
	v_add_u32_e32 v12, 0x1c4, v82
	v_lshlrev_b32_e32 v13, 7, v12
	v_bfe_u32 v12, v12, 3, 2
	v_bitop3_b32 v14, v12, v81, v83 bitop3:0x36
	v_lshlrev_b32_e32 v14, 4, v14
	v_add3_u32 v14, 0, v14, v13
	ds_read_b128 v[92:95], v14
	v_bitop3_b32 v12, v12, v86, v83 bitop3:0x36
	v_lshlrev_b32_e32 v12, 4, v12
	v_add3_u32 v12, 0, v12, v13
	ds_read_b128 v[96:99], v12
	v_mfma_f32_16x16x32_bf16 v[12:15], v[88:91], v[0:3], v[8:11]
	v_add_u32_e32 v89, 0x22100, v80
	s_waitcnt lgkmcnt(1)
	v_mfma_f32_16x16x32_bf16 v[8:11], v[92:95], v[4:7], 0
	v_or_b32_e32 v95, s18, v79
	v_med3_u32 v80, v95, 8, 56
	v_add_u32_e32 v94, -8, v80
	s_waitcnt lgkmcnt(0)
	v_mfma_f32_16x16x32_bf16 v[8:11], v[96:99], v[0:3], v[8:11]
	s_barrier
	s_lshr_b32 s0, s21, 4
	s_mov_b32 s1, 0
	s_cmpk_gt_u32 s93, 0x123f
	s_cbranch_scc1 .Lvse_skip
	s_add_i32 s4, s24, 0xffffff00
	s_lshl_b32 s6, s20, 7
	s_lshl_b32 s5, s0, 6
	s_mul_i32 s8, s0, 0x44000
	s_mul_hi_u32 s5, s5, 0x1100
	s_add_u32 s8, s50, s8
	s_addc_u32 s9, s51, s5
	s_mov_b32 s5, s1
	s_lshl_b64 s[4:5], s[4:5], 1
	s_add_u32 s4, s8, s4
	s_movk_i32 s7, 0x1100
	s_addc_u32 s5, s9, s5
	v_lshl_add_u32 v184, v85, 4, s3
	s_add_i32 s8, s94, -8
	s_mov_b32 s9, 0xe070381d
	s_movk_i32 s10, 0xfb70
	s_mov_b32 s11, 0x12400
	s_mov_b32 s12, s67
.Lvse_loop:
	v_mul_hi_i32 v185, v184, s9
	v_add_u32_e32 v185, v185, v184
	v_lshrrev_b32_e32 v186, 31, v185
	v_ashrrev_i32_e32 v185, 10, v185
	v_add_u32_e32 v185, v185, v186
	v_mad_i32_i24 v186, v185, s10, v184
	v_cmp_gt_i32_e32 vcc, s11, v184
	v_mov_b64_e32 v[188:189], s[4:5]
	v_min_i32_e32 v185, 63, v185
	v_cndmask_b32_e32 v186, 0, v186, vcc
	v_mad_i64_i32 v[188:189], s[14:15], v185, s7, v[188:189]
	v_ashrrev_i32_e32 v185, 1, v186
	v_cmp_gt_i32_e32 vcc, s6, v186
	s_mov_b32 m0, s12
	s_addk_i32 s12, 0x2000
	v_cndmask_b32_e32 v190, 0, v185, vcc
	v_ashrrev_i32_e32 v191, 31, v190
	v_lshl_add_u64 v[188:189], v[190:191], 1, v[188:189]
	global_load_lds_dwordx4 v[188:189], off
	s_add_i32 s8, s8, 8
	s_cmpk_lt_u32 s8, 0x41
	v_add_u32_e32 v184, 0x2000, v184
	s_cbranch_scc1 .Lvse_loop
.Lvse_skip:
	v_lshl_add_u32 v97, v81, 3, v84
	v_add_u32_e32 v96, 8, v80
	v_sub_u32_e32 v80, v97, v95
	v_med3_i32 v80, v80, -15, 15
	v_cmp_ge_i32_e32 vcc, v97, v94
	v_cmp_lt_i32_e64 s[0:1], v97, v96
	v_add_u32_e32 v80, 15, v80
	s_and_b64 vcc, vcc, s[0:1]
	v_cndmask_b32_e32 v82, -1, v80, vcc
	v_cmp_lt_i32_e32 vcc, -1, v82
	v_mov_b32_e32 v80, 0xf149f2ca
	v_lshl_add_u32 v82, v82, 2, v89
	s_and_saveexec_b64 s[0:1], vcc
	s_cbranch_execz .LBB0_1441
	ds_read_b32 v91, v82 offset:372
	s_mov_b32 s4, 0x3e38aa3b
	v_mov_b32_e32 v90, v68
	s_mov_b32 s5, 0x3fb8aa3b
	s_waitcnt lgkmcnt(0)
	v_pk_mul_f32 v[90:91], v[90:91], s[4:5]
	s_nop 0
	v_add_f32_e32 v87, v90, v91

.LBB0_1567:
	s_or_b64 exec, exec, s[0:1]
	s_mov_b32 s0, 0xff61b1e6
	v_max3_f32 v10, v87, s0, v80
	v_max3_f32 v10, v10, v69, v68
	v_max3_f32 v10, v10, v71, v70
	v_max3_f32 v10, v10, v65, v64
	v_max3_f32 v10, v10, v67, v66
	v_max3_f32 v10, v10, v61, v60
	v_max3_f32 v10, v10, v63, v62
	v_max3_f32 v10, v10, v89, v56
	v_max3_f32 v10, v10, v58, v57
	v_max3_f32 v10, v10, v53, v52
	v_max3_f32 v10, v10, v55, v54
	v_max3_f32 v10, v10, v59, v48
	v_max3_f32 v10, v10, v50, v49
	v_max3_f32 v10, v10, v45, v44
	v_max3_f32 v10, v10, v47, v46
	v_max3_f32 v10, v10, v51, v40
	v_max3_f32 v10, v10, v42, v41
	v_max3_f32 v10, v10, v37, v36
	v_max3_f32 v10, v10, v39, v38
	v_max3_f32 v10, v10, v43, v32
	v_max3_f32 v10, v10, v34, v33
	v_max3_f32 v10, v10, v29, v28
	v_max3_f32 v10, v10, v31, v30
	v_max3_f32 v10, v10, v35, v24
	v_max3_f32 v10, v10, v26, v25
	v_max3_f32 v10, v10, v21, v20
	v_mbcnt_lo_u32_b32 v11, -1, 0
	v_max3_f32 v10, v10, v23, v22
	v_mbcnt_hi_u32_b32 v11, -1, v11
	v_max3_f32 v10, v10, v27, v17
	v_and_b32_e32 v82, 64, v11
	v_max3_f32 v10, v10, v18, v16
	v_xor_b32_e32 v19, 16, v11
	v_add_u32_e32 v82, 64, v82
	v_max3_f32 v10, v10, v13, v12
	v_cmp_lt_i32_e32 vcc, v19, v82
	v_max3_f32 v10, v10, v15, v14
	v_max3_f32 v10, v10, v9, v8
	v_cndmask_b32_e32 v19, v11, v19, vcc
	v_lshlrev_b32_e32 v83, 2, v19
	ds_bpermute_b32 v19, v83, v10
	s_lshr_b32 s0, s21, 4
	s_waitcnt vmcnt(0) lgkmcnt(0)
	s_cmpk_lt_u32 s93, 0x1240
	s_cselect_b64 s[68:69], -1, 0
	s_waitcnt lgkmcnt(0)
	v_max_f32_e32 v19, v19, v19
	v_max_f32_e32 v10, v10, v19
	v_xor_b32_e32 v19, 32, v11
	v_cmp_lt_i32_e32 vcc, v19, v82
	s_cmpk_gt_u32 s93, 0x123f
	s_mov_b32 s1, 0
	v_cndmask_b32_e32 v11, v11, v19, vcc
	v_lshlrev_b32_e32 v82, 2, v11
	ds_bpermute_b32 v11, v82, v10
	v_lshl_add_u32 v91, v85, 4, s3
	s_waitcnt lgkmcnt(0)
	s_barrier
	v_max_f32_e32 v11, v11, v11
	v_max_f32_e32 v88, v10, v11
	s_branch .LBB0_1570
	s_add_i32 s4, s24, 0xffffff00
	s_lshl_b32 s6, s20, 7
	s_lshl_b32 s5, s0, 6
	s_mul_i32 s8, s0, 0x44000
	s_mul_hi_u32 s5, s5, 0x1100
	s_add_u32 s8, s50, s8
	s_addc_u32 s9, s51, s5
	s_mov_b32 s5, s1
	s_lshl_b64 s[4:5], s[4:5], 1
	s_add_u32 s4, s8, s4
	s_movk_i32 s7, 0x1100
	s_addc_u32 s5, s9, s5
	v_lshl_add_u32 v10, v85, 4, s3
	s_add_i32 s8, s94, -8
	s_mov_b32 s9, 0xe070381d
	s_movk_i32 s10, 0xfb70
	s_mov_b32 s11, 0x12400
	s_mov_b32 s12, s67
